# g1: latent kv / rope-key tiles published with write-through stores, no L2 write-back before the counter arrival
# speedup vs baseline: 1.0364x; 1.0060x over previous
.LBB0_303:
	s_and_b32 s85, s76, 63
	v_mov_b32_e32 v156, v0
	s_lshl_b32 s83, s85, 7
	s_ashr_i32 s84, s77, 6
	s_cmp_gt_i32 s84, 19
	v_ashrrev_i32_e32 v2, 1, v156
	v_and_b32_e32 v174, 31, v156
	v_bfe_u32 v172, v156, 5, 1
	v_bfe_u32 v173, v156, 6, 1
	v_and_b32_e32 v175, 0xffffffc0, v2
	s_mov_b64 s[0:1], -1
	v_mov_b32_e32 v197, v188
	s_cbranch_scc1 .LBB0_420
	s_and_b32 s0, s75, 63
	s_lshl_b32 s62, s0, 7
	s_cmp_lt_u32 s85, 32
	s_cselect_b64 s[2:3], -1, 0
	s_lshr_b32 s42, s85, 1
	s_and_b32 s4, s83, 0x780
	s_and_b32 s6, s83, 0x80
	v_lshlrev_b32_e32 v2, 4, v172
	s_cmp_gt_u32 s85, 31
	v_or_b32_e32 v132, v175, v174
	v_lshl_or_b32 v2, v173, 8, v2
	s_movk_i32 s0, 0x210
	s_cselect_b64 s[34:35], -1, 0
	v_mad_u64_u32 v[132:133], s[0:1], v132, s0, v[2:3]
	s_and_b64 s[0:1], s[34:35], exec
	s_cselect_b32 s86, s4, s6
	s_cmp_gt_i32 s84, 13
	s_mov_b64 s[0:1], -1
	ds_write_b128 v132, v[52:55]
	ds_write_b128 v132, v[56:59] offset:32
	ds_write_b128 v132, v[60:63] offset:64
	ds_write_b128 v132, v[64:67] offset:96
	ds_write_b128 v132, v[36:39] offset:128
	ds_write_b128 v132, v[40:43] offset:160
	ds_write_b128 v132, v[44:47] offset:192
	ds_write_b128 v132, v[48:51] offset:224
	ds_write_b128 v132, v[20:23] offset:16896
	ds_write_b128 v132, v[24:27] offset:16928
	ds_write_b128 v132, v[28:31] offset:16960
	ds_write_b128 v132, v[32:35] offset:16992
	ds_write_b128 v132, v[4:7] offset:17024
	ds_write_b128 v132, v[8:11] offset:17056
	ds_write_b128 v132, v[12:15] offset:17088
	ds_write_b128 v132, v[16:19] offset:17120
	s_waitcnt lgkmcnt(0)
	s_barrier
	s_cbranch_scc0 .LBB0_363
	s_cmp_gt_u32 s84, 17
	s_cbranch_scc0 .LBB0_351
	s_cmp_eq_u32 s84, 18
	v_lshlrev_b32_e32 v136, 2, v156
	s_cbranch_scc1 .LBB0_316
	v_ashrrev_i32_e32 v138, 3, v156
	v_and_b32_e32 v2, 28, v136
	s_movk_i32 s4, 0x210
	v_lshlrev_b32_e32 v2, 2, v2
	v_mul_lo_u32 v132, v138, s4
	v_add_u32_e32 v137, v2, v132
	ds_read_b128 v[132:135], v137
	s_lshl_b32 s0, s42, 2
	s_add_i32 s0, s0, s94
	s_ashr_i32 s1, s0, 31
	s_lshl_b64 s[4:5], s[0:1], 15
	s_and_b64 vcc, exec, s[2:3]
	s_cbranch_vccz .LBB0_309
	v_add_u32_e32 v140, s6, v138
	v_readlane_b32 s0, v251, 26
	v_ashrrev_i32_e32 v141, 31, v140
	s_add_u32 s0, s0, s4
	v_readlane_b32 s1, v251, 27
	s_addc_u32 s1, s1, s5
	v_lshlrev_b64 v[140:141], 7, v[140:141]
	v_lshl_add_u64 v[140:141], s[0:1], 0, v[140:141]
	v_lshl_add_u64 v[140:141], v[140:141], 0, v[2:3]
	s_waitcnt lgkmcnt(0)
	global_store_dwordx4 v[140:141], v[132:135], off sc1
.LBB0_309:
	v_add_u32_e32 v140, s83, v138
	v_ashrrev_i32_e32 v141, 31, v140
	v_readlane_b32 s12, v252, 47
	v_lshlrev_b64 v[140:141], 7, v[140:141]
	v_readlane_b32 s14, v252, 49
	v_readlane_b32 s15, v252, 50
	v_cndmask_b32_e64 v139, 0, 1, s[2:3]
	v_cmp_ne_u32_e64 s[0:1], 1, v139
	v_lshl_add_u64 v[140:141], s[14:15], 0, v[140:141]
	v_lshl_add_u64 v[140:141], v[140:141], 0, v[2:3]
	s_waitcnt lgkmcnt(0)
	global_store_dwordx4 v[140:141], v[132:135], off sc1
	ds_read_b128 v[132:135], v137 offset:16896
	s_andn2_b64 vcc, exec, s[2:3]
	v_add_u32_e32 v139, 32, v138
	v_readlane_b32 s13, v252, 48
	v_readlane_b32 s16, v252, 51
	v_readlane_b32 s17, v252, 52
	v_readlane_b32 s18, v252, 53
	v_readlane_b32 s19, v252, 54
	s_cbranch_vccnz .LBB0_311
	v_add_u32_e32 v140, s6, v139
	v_readlane_b32 s7, v251, 26
	v_ashrrev_i32_e32 v141, 31, v140
	s_add_u32 s8, s7, s4
	v_readlane_b32 s7, v251, 27
	s_addc_u32 s9, s7, s5
	v_lshlrev_b64 v[140:141], 7, v[140:141]
	v_lshl_add_u64 v[140:141], s[8:9], 0, v[140:141]
	v_lshl_add_u64 v[140:141], v[140:141], 0, v[2:3]
	s_waitcnt lgkmcnt(0)
	global_store_dwordx4 v[140:141], v[132:135], off sc1
.LBB0_311:
	v_add_u32_e32 v140, s83, v139
	v_ashrrev_i32_e32 v141, 31, v140
	v_readlane_b32 s12, v252, 47
	v_lshlrev_b64 v[140:141], 7, v[140:141]
	v_readlane_b32 s14, v252, 49
	v_readlane_b32 s15, v252, 50
	v_add_u32_e32 v139, 64, v138
	s_and_b64 vcc, exec, s[0:1]
	v_lshl_add_u64 v[140:141], s[14:15], 0, v[140:141]
	v_lshl_add_u64 v[140:141], v[140:141], 0, v[2:3]
	s_waitcnt lgkmcnt(0)
	global_store_dwordx4 v[140:141], v[132:135], off sc1
	ds_read_b128 v[132:135], v137 offset:33792
	v_readlane_b32 s13, v252, 48
	v_readlane_b32 s16, v252, 51
	v_readlane_b32 s17, v252, 52
	v_readlane_b32 s18, v252, 53
	v_readlane_b32 s19, v252, 54
	s_cbranch_vccnz .LBB0_313
	v_add_u32_e32 v140, s6, v139
	v_readlane_b32 s7, v251, 26
	v_ashrrev_i32_e32 v141, 31, v140
	s_add_u32 s8, s7, s4
	v_readlane_b32 s7, v251, 27
	s_addc_u32 s9, s7, s5
	v_lshlrev_b64 v[140:141], 7, v[140:141]
	v_lshl_add_u64 v[140:141], s[8:9], 0, v[140:141]
	v_lshl_add_u64 v[140:141], v[140:141], 0, v[2:3]
	s_waitcnt lgkmcnt(0)
	global_store_dwordx4 v[140:141], v[132:135], off sc1
.LBB0_313:
	v_add_u32_e32 v140, s83, v139
	v_ashrrev_i32_e32 v141, 31, v140
	v_readlane_b32 s12, v252, 47
	v_lshlrev_b64 v[140:141], 7, v[140:141]
	v_readlane_b32 s14, v252, 49
	v_readlane_b32 s15, v252, 50
	v_add_u32_e32 v138, 0x60, v138
	s_and_b64 vcc, exec, s[0:1]
	v_lshl_add_u64 v[140:141], s[14:15], 0, v[140:141]
	v_lshl_add_u64 v[140:141], v[140:141], 0, v[2:3]
	s_waitcnt lgkmcnt(0)
	global_store_dwordx4 v[140:141], v[132:135], off sc1
	ds_read_b128 v[132:135], v137 offset:50688
	v_readlane_b32 s13, v252, 48
	v_readlane_b32 s16, v252, 51
	v_readlane_b32 s17, v252, 52
	v_readlane_b32 s18, v252, 53
	v_readlane_b32 s19, v252, 54
	s_cbranch_vccnz .LBB0_315
	v_add_u32_e32 v140, s6, v138
	v_readlane_b32 s0, v251, 26
	v_ashrrev_i32_e32 v141, 31, v140
	s_add_u32 s0, s0, s4
	v_readlane_b32 s1, v251, 27
	s_addc_u32 s1, s1, s5
	v_lshlrev_b64 v[140:141], 7, v[140:141]
	v_lshl_add_u64 v[140:141], s[0:1], 0, v[140:141]
	v_lshl_add_u64 v[140:141], v[140:141], 0, v[2:3]
	s_waitcnt lgkmcnt(0)
	global_store_dwordx4 v[140:141], v[132:135], off sc1
.LBB0_315:
	v_add_u32_e32 v138, s83, v138
	v_ashrrev_i32_e32 v139, 31, v138
	v_readlane_b32 s12, v252, 47
	v_lshlrev_b64 v[138:139], 7, v[138:139]
	v_readlane_b32 s14, v252, 49
	v_readlane_b32 s15, v252, 50
	s_mov_b64 s[0:1], 0
	v_readlane_b32 s13, v252, 48
	v_lshl_add_u64 v[138:139], s[14:15], 0, v[138:139]
	v_lshl_add_u64 v[138:139], v[138:139], 0, v[2:3]
	v_readlane_b32 s16, v252, 51
	v_readlane_b32 s17, v252, 52
	v_readlane_b32 s18, v252, 53
	v_readlane_b32 s19, v252, 54
	s_waitcnt lgkmcnt(0)
	global_store_dwordx4 v[138:139], v[132:135], off sc1

.LBB0_319:
	v_add_u32_e32 v158, s83, v142
	v_ashrrev_i32_e32 v159, 31, v158
	v_readlane_b32 s12, v253, 2
	v_lshlrev_b64 v[158:159], 8, v[158:159]
	v_readlane_b32 s18, v253, 8
	v_readlane_b32 s19, v253, 9
	v_lshlrev_b32_e32 v2, 1, v2
	v_cvt_pk_bf16_f32 v136, v136, v137
	v_lshl_add_u64 v[158:159], s[18:19], 0, v[158:159]
	v_lshl_add_u64 v[158:159], v[158:159], 0, v[2:3]
	v_cvt_pk_bf16_f32 v137, v138, v139
	global_store_dwordx2 v[158:159], v[136:137], off sc1
	ds_read_b128 v[136:139], v157 offset:4224
	v_add_u32_e32 v158, 8, v142
	v_readlane_b32 s13, v253, 3
	v_readlane_b32 s14, v253, 4
	v_readlane_b32 s15, v253, 5
	s_waitcnt lgkmcnt(0)
	v_pk_mul_f32 v[162:163], v[136:137], v[136:137]
	v_pk_mul_f32 v[160:161], v[138:139], v[138:139]
	v_add_f32_e32 v141, v162, v163
	v_add_f32_e32 v141, v160, v141
	v_add_f32_e32 v141, v161, v141
	s_nop 1
	v_readlane_b32 s16, v253, 6
	v_readlane_b32 s17, v253, 7
	s_waitcnt lgkmcnt(0)
	v_add_f32_dpp v141, v141, v141 quad_perm:[1,0,3,2] row_mask:0xf bank_mask:0xf
	s_nop 1
	s_waitcnt lgkmcnt(0)
	v_add_f32_dpp v141, v141, v141 quad_perm:[2,3,0,1] row_mask:0xf bank_mask:0xf
	s_nop 1
	s_waitcnt lgkmcnt(0)
	v_add_f32_dpp v141, v141, v141 row_half_mirror row_mask:0xf bank_mask:0xf
	s_nop 1
	s_waitcnt lgkmcnt(0)
	v_add_f32_dpp v141, v141, v141 row_mirror row_mask:0xf bank_mask:0xf
	v_mov_b32_e32 v159, v141
	s_nop 1
	v_permlane16_swap_b32_e32 v159, v141
	s_waitcnt lgkmcnt(0)
	v_add_f32_e32 v141, v141, v159
	v_fmamk_f32 v141, v141, 0x3c000000, v1
	v_cmp_gt_f32_e32 vcc, s29, v141
	v_mul_f32_e32 v159, 0x4b800000, v141
	s_nop 0
	v_cndmask_b32_e32 v141, v141, v159, vcc
	v_rsq_f32_e32 v141, v141
	s_nop 0
	v_mul_f32_e32 v159, 0x45800000, v141
	v_cndmask_b32_e32 v160, v141, v159, vcc
	v_pk_mul_f32 v[136:137], v[136:137], v[160:161] op_sel_hi:[1,0]
	v_pk_mul_f32 v[138:139], v[138:139], v[160:161] op_sel_hi:[1,0]
	v_pk_mul_f32 v[136:137], v[132:133], v[136:137]
	v_pk_mul_f32 v[138:139], v[134:135], v[138:139]
	s_and_b64 vcc, exec, s[38:39]
	s_cbranch_vccnz .LBB0_321
	v_add_u32_e32 v160, s6, v158
	v_readlane_b32 s0, v251, 28
	v_ashrrev_i32_e32 v161, 31, v160
	s_add_u32 s0, s0, s4
	v_readlane_b32 s1, v251, 29
	s_addc_u32 s1, s1, s5
	v_lshlrev_b64 v[160:161], 9, v[160:161]
	v_lshl_add_u64 v[160:161], s[0:1], 0, v[160:161]
	v_mov_b32_e32 v141, v3
	v_lshl_add_u64 v[160:161], v[160:161], 0, v[140:141]
	global_store_dwordx4 v[160:161], v[136:139], off
.LBB0_321:
	v_add_u32_e32 v158, s83, v158
	v_ashrrev_i32_e32 v159, 31, v158
	v_readlane_b32 s12, v253, 2
	v_lshlrev_b64 v[158:159], 8, v[158:159]
	v_readlane_b32 s18, v253, 8
	v_readlane_b32 s19, v253, 9
	v_cvt_pk_bf16_f32 v136, v136, v137
	v_cvt_pk_bf16_f32 v137, v138, v139
	v_lshl_add_u64 v[158:159], s[18:19], 0, v[158:159]
	v_lshl_add_u64 v[158:159], v[158:159], 0, v[2:3]
	global_store_dwordx2 v[158:159], v[136:137], off sc1
	ds_read_b128 v[136:139], v157 offset:8448
	v_add_u32_e32 v158, 16, v142
	v_readlane_b32 s13, v253, 3
	v_readlane_b32 s14, v253, 4
	v_readlane_b32 s15, v253, 5
	s_waitcnt lgkmcnt(0)
	v_pk_mul_f32 v[162:163], v[136:137], v[136:137]
	v_pk_mul_f32 v[160:161], v[138:139], v[138:139]
	v_add_f32_e32 v141, v162, v163
	v_add_f32_e32 v141, v160, v141
	v_add_f32_e32 v141, v161, v141
	s_nop 1
	v_readlane_b32 s16, v253, 6
	v_readlane_b32 s17, v253, 7
	s_waitcnt lgkmcnt(0)
	v_add_f32_dpp v141, v141, v141 quad_perm:[1,0,3,2] row_mask:0xf bank_mask:0xf
	s_nop 1
	s_waitcnt lgkmcnt(0)
	v_add_f32_dpp v141, v141, v141 quad_perm:[2,3,0,1] row_mask:0xf bank_mask:0xf
	s_nop 1
	s_waitcnt lgkmcnt(0)
	v_add_f32_dpp v141, v141, v141 row_half_mirror row_mask:0xf bank_mask:0xf
	s_nop 1
	s_waitcnt lgkmcnt(0)
	v_add_f32_dpp v141, v141, v141 row_mirror row_mask:0xf bank_mask:0xf
	v_mov_b32_e32 v159, v141
	s_nop 1
	v_permlane16_swap_b32_e32 v159, v141
	s_waitcnt lgkmcnt(0)
	v_add_f32_e32 v141, v141, v159
	v_fmamk_f32 v141, v141, 0x3c000000, v1
	v_cmp_gt_f32_e32 vcc, s29, v141
	v_mul_f32_e32 v159, 0x4b800000, v141
	s_nop 0
	v_cndmask_b32_e32 v141, v141, v159, vcc
	v_rsq_f32_e32 v141, v141
	s_nop 0
	v_mul_f32_e32 v159, 0x45800000, v141
	v_cndmask_b32_e32 v160, v141, v159, vcc
	v_pk_mul_f32 v[136:137], v[136:137], v[160:161] op_sel_hi:[1,0]
	v_pk_mul_f32 v[138:139], v[138:139], v[160:161] op_sel_hi:[1,0]
	v_pk_mul_f32 v[136:137], v[132:133], v[136:137]
	v_pk_mul_f32 v[138:139], v[134:135], v[138:139]
	s_and_b64 vcc, exec, s[38:39]
	s_cbranch_vccnz .LBB0_323
	v_add_u32_e32 v160, s6, v158
	v_readlane_b32 s0, v251, 28
	v_ashrrev_i32_e32 v161, 31, v160
	s_add_u32 s0, s0, s4
	v_readlane_b32 s1, v251, 29
	s_addc_u32 s1, s1, s5
	v_lshlrev_b64 v[160:161], 9, v[160:161]
	v_lshl_add_u64 v[160:161], s[0:1], 0, v[160:161]
	v_mov_b32_e32 v141, v3
	v_lshl_add_u64 v[160:161], v[160:161], 0, v[140:141]
	global_store_dwordx4 v[160:161], v[136:139], off
.LBB0_323:
	v_add_u32_e32 v158, s83, v158
	v_ashrrev_i32_e32 v159, 31, v158
	v_readlane_b32 s12, v253, 2
	v_lshlrev_b64 v[158:159], 8, v[158:159]
	v_readlane_b32 s18, v253, 8
	v_readlane_b32 s19, v253, 9
	v_cvt_pk_bf16_f32 v136, v136, v137
	v_cvt_pk_bf16_f32 v137, v138, v139
	v_lshl_add_u64 v[158:159], s[18:19], 0, v[158:159]
	v_lshl_add_u64 v[158:159], v[158:159], 0, v[2:3]
	global_store_dwordx2 v[158:159], v[136:137], off sc1
	ds_read_b128 v[136:139], v157 offset:12672
	v_add_u32_e32 v158, 24, v142
	v_readlane_b32 s13, v253, 3
	v_readlane_b32 s14, v253, 4
	v_readlane_b32 s15, v253, 5
	s_waitcnt lgkmcnt(0)
	v_pk_mul_f32 v[162:163], v[136:137], v[136:137]
	v_pk_mul_f32 v[160:161], v[138:139], v[138:139]
	v_add_f32_e32 v141, v162, v163
	v_add_f32_e32 v141, v160, v141
	v_add_f32_e32 v141, v161, v141
	s_nop 1
	v_readlane_b32 s16, v253, 6
	v_readlane_b32 s17, v253, 7
	s_waitcnt lgkmcnt(0)
	v_add_f32_dpp v141, v141, v141 quad_perm:[1,0,3,2] row_mask:0xf bank_mask:0xf
	s_nop 1
	s_waitcnt lgkmcnt(0)
	v_add_f32_dpp v141, v141, v141 quad_perm:[2,3,0,1] row_mask:0xf bank_mask:0xf
	s_nop 1
	s_waitcnt lgkmcnt(0)
	v_add_f32_dpp v141, v141, v141 row_half_mirror row_mask:0xf bank_mask:0xf
	s_nop 1
	s_waitcnt lgkmcnt(0)
	v_add_f32_dpp v141, v141, v141 row_mirror row_mask:0xf bank_mask:0xf
	v_mov_b32_e32 v159, v141
	s_nop 1
	v_permlane16_swap_b32_e32 v159, v141
	s_waitcnt lgkmcnt(0)
	v_add_f32_e32 v141, v141, v159
	v_fmamk_f32 v141, v141, 0x3c000000, v1
	v_cmp_gt_f32_e32 vcc, s29, v141
	v_mul_f32_e32 v159, 0x4b800000, v141
	s_nop 0
	v_cndmask_b32_e32 v141, v141, v159, vcc
	v_rsq_f32_e32 v141, v141
	s_nop 0
	v_mul_f32_e32 v159, 0x45800000, v141
	v_cndmask_b32_e32 v160, v141, v159, vcc
	v_pk_mul_f32 v[136:137], v[136:137], v[160:161] op_sel_hi:[1,0]
	v_pk_mul_f32 v[138:139], v[138:139], v[160:161] op_sel_hi:[1,0]
	v_pk_mul_f32 v[136:137], v[132:133], v[136:137]
	v_pk_mul_f32 v[138:139], v[134:135], v[138:139]
	s_and_b64 vcc, exec, s[38:39]
	s_cbranch_vccnz .LBB0_325
	v_add_u32_e32 v160, s6, v158
	v_readlane_b32 s0, v251, 28
	v_ashrrev_i32_e32 v161, 31, v160
	s_add_u32 s0, s0, s4
	v_readlane_b32 s1, v251, 29
	s_addc_u32 s1, s1, s5
	v_lshlrev_b64 v[160:161], 9, v[160:161]
	v_lshl_add_u64 v[160:161], s[0:1], 0, v[160:161]
	v_mov_b32_e32 v141, v3
	v_lshl_add_u64 v[160:161], v[160:161], 0, v[140:141]
	global_store_dwordx4 v[160:161], v[136:139], off
.LBB0_325:
	v_add_u32_e32 v158, s83, v158
	v_ashrrev_i32_e32 v159, 31, v158
	v_readlane_b32 s12, v253, 2
	v_lshlrev_b64 v[158:159], 8, v[158:159]
	v_readlane_b32 s18, v253, 8
	v_readlane_b32 s19, v253, 9
	v_cvt_pk_bf16_f32 v136, v136, v137
	v_cvt_pk_bf16_f32 v137, v138, v139
	v_lshl_add_u64 v[158:159], s[18:19], 0, v[158:159]
	v_lshl_add_u64 v[158:159], v[158:159], 0, v[2:3]
	global_store_dwordx2 v[158:159], v[136:137], off sc1
	ds_read_b128 v[136:139], v157 offset:16896
	v_add_u32_e32 v158, 32, v142
	v_readlane_b32 s13, v253, 3
	v_readlane_b32 s14, v253, 4
	v_readlane_b32 s15, v253, 5
	s_waitcnt lgkmcnt(0)
	v_pk_mul_f32 v[162:163], v[136:137], v[136:137]
	v_pk_mul_f32 v[160:161], v[138:139], v[138:139]
	v_add_f32_e32 v141, v162, v163
	v_add_f32_e32 v141, v160, v141
	v_add_f32_e32 v141, v161, v141
	s_nop 1
	v_readlane_b32 s16, v253, 6
	v_readlane_b32 s17, v253, 7
	s_waitcnt lgkmcnt(0)
	v_add_f32_dpp v141, v141, v141 quad_perm:[1,0,3,2] row_mask:0xf bank_mask:0xf
	s_nop 1
	s_waitcnt lgkmcnt(0)
	v_add_f32_dpp v141, v141, v141 quad_perm:[2,3,0,1] row_mask:0xf bank_mask:0xf
	s_nop 1
	s_waitcnt lgkmcnt(0)
	v_add_f32_dpp v141, v141, v141 row_half_mirror row_mask:0xf bank_mask:0xf
	s_nop 1
	s_waitcnt lgkmcnt(0)
	v_add_f32_dpp v141, v141, v141 row_mirror row_mask:0xf bank_mask:0xf
	v_mov_b32_e32 v159, v141
	s_nop 1
	v_permlane16_swap_b32_e32 v159, v141
	s_waitcnt lgkmcnt(0)
	v_add_f32_e32 v141, v141, v159
	v_fmamk_f32 v141, v141, 0x3c000000, v1
	v_cmp_gt_f32_e32 vcc, s29, v141
	v_mul_f32_e32 v159, 0x4b800000, v141
	s_nop 0
	v_cndmask_b32_e32 v141, v141, v159, vcc
	v_rsq_f32_e32 v141, v141
	s_nop 0
	v_mul_f32_e32 v159, 0x45800000, v141
	v_cndmask_b32_e32 v160, v141, v159, vcc
	v_pk_mul_f32 v[136:137], v[136:137], v[160:161] op_sel_hi:[1,0]
	v_pk_mul_f32 v[138:139], v[138:139], v[160:161] op_sel_hi:[1,0]
	v_pk_mul_f32 v[136:137], v[132:133], v[136:137]
	v_pk_mul_f32 v[138:139], v[134:135], v[138:139]
	s_and_b64 vcc, exec, s[38:39]
	s_cbranch_vccnz .LBB0_327
	v_add_u32_e32 v160, s6, v158
	v_readlane_b32 s0, v251, 28
	v_ashrrev_i32_e32 v161, 31, v160
	s_add_u32 s0, s0, s4
	v_readlane_b32 s1, v251, 29
	s_addc_u32 s1, s1, s5
	v_lshlrev_b64 v[160:161], 9, v[160:161]
	v_lshl_add_u64 v[160:161], s[0:1], 0, v[160:161]
	v_mov_b32_e32 v141, v3
	v_lshl_add_u64 v[160:161], v[160:161], 0, v[140:141]
	global_store_dwordx4 v[160:161], v[136:139], off
.LBB0_327:
	v_add_u32_e32 v158, s83, v158
	v_ashrrev_i32_e32 v159, 31, v158
	v_readlane_b32 s12, v253, 2
	v_lshlrev_b64 v[158:159], 8, v[158:159]
	v_readlane_b32 s18, v253, 8
	v_readlane_b32 s19, v253, 9
	v_cvt_pk_bf16_f32 v136, v136, v137
	v_cvt_pk_bf16_f32 v137, v138, v139
	v_lshl_add_u64 v[158:159], s[18:19], 0, v[158:159]
	v_lshl_add_u64 v[158:159], v[158:159], 0, v[2:3]
	global_store_dwordx2 v[158:159], v[136:137], off sc1
	ds_read_b128 v[136:139], v157 offset:21120
	v_add_u32_e32 v158, 40, v142
	v_readlane_b32 s13, v253, 3
	v_readlane_b32 s14, v253, 4
	v_readlane_b32 s15, v253, 5
	s_waitcnt lgkmcnt(0)
	v_pk_mul_f32 v[162:163], v[136:137], v[136:137]
	v_pk_mul_f32 v[160:161], v[138:139], v[138:139]
	v_add_f32_e32 v141, v162, v163
	v_add_f32_e32 v141, v160, v141
	v_add_f32_e32 v141, v161, v141
	s_nop 1
	v_readlane_b32 s16, v253, 6
	v_readlane_b32 s17, v253, 7
	s_waitcnt lgkmcnt(0)
	v_add_f32_dpp v141, v141, v141 quad_perm:[1,0,3,2] row_mask:0xf bank_mask:0xf
	s_nop 1
	s_waitcnt lgkmcnt(0)
	v_add_f32_dpp v141, v141, v141 quad_perm:[2,3,0,1] row_mask:0xf bank_mask:0xf
	s_nop 1
	s_waitcnt lgkmcnt(0)
	v_add_f32_dpp v141, v141, v141 row_half_mirror row_mask:0xf bank_mask:0xf
	s_nop 1
	s_waitcnt lgkmcnt(0)
	v_add_f32_dpp v141, v141, v141 row_mirror row_mask:0xf bank_mask:0xf
	v_mov_b32_e32 v159, v141
	s_nop 1
	v_permlane16_swap_b32_e32 v159, v141
	s_waitcnt lgkmcnt(0)
	v_add_f32_e32 v141, v141, v159
	v_fmamk_f32 v141, v141, 0x3c000000, v1
	v_cmp_gt_f32_e32 vcc, s29, v141
	v_mul_f32_e32 v159, 0x4b800000, v141
	s_nop 0
	v_cndmask_b32_e32 v141, v141, v159, vcc
	v_rsq_f32_e32 v141, v141
	s_nop 0
	v_mul_f32_e32 v159, 0x45800000, v141
	v_cndmask_b32_e32 v160, v141, v159, vcc
	v_pk_mul_f32 v[136:137], v[136:137], v[160:161] op_sel_hi:[1,0]
	v_pk_mul_f32 v[138:139], v[138:139], v[160:161] op_sel_hi:[1,0]
	v_pk_mul_f32 v[136:137], v[132:133], v[136:137]
	v_pk_mul_f32 v[138:139], v[134:135], v[138:139]
	s_and_b64 vcc, exec, s[38:39]
	s_cbranch_vccnz .LBB0_329
	v_add_u32_e32 v160, s6, v158
	v_readlane_b32 s0, v251, 28
	v_ashrrev_i32_e32 v161, 31, v160
	s_add_u32 s0, s0, s4
	v_readlane_b32 s1, v251, 29
	s_addc_u32 s1, s1, s5
	v_lshlrev_b64 v[160:161], 9, v[160:161]
	v_lshl_add_u64 v[160:161], s[0:1], 0, v[160:161]
	v_mov_b32_e32 v141, v3
	v_lshl_add_u64 v[160:161], v[160:161], 0, v[140:141]
	global_store_dwordx4 v[160:161], v[136:139], off
.LBB0_329:
	v_add_u32_e32 v158, s83, v158
	v_ashrrev_i32_e32 v159, 31, v158
	v_readlane_b32 s12, v253, 2
	v_lshlrev_b64 v[158:159], 8, v[158:159]
	v_readlane_b32 s18, v253, 8
	v_readlane_b32 s19, v253, 9
	v_cvt_pk_bf16_f32 v136, v136, v137
	v_cvt_pk_bf16_f32 v137, v138, v139
	v_lshl_add_u64 v[158:159], s[18:19], 0, v[158:159]
	v_lshl_add_u64 v[158:159], v[158:159], 0, v[2:3]
	global_store_dwordx2 v[158:159], v[136:137], off sc1
	ds_read_b128 v[136:139], v157 offset:25344
	v_add_u32_e32 v158, 48, v142
	v_readlane_b32 s13, v253, 3
	v_readlane_b32 s14, v253, 4
	v_readlane_b32 s15, v253, 5
	s_waitcnt lgkmcnt(0)
	v_pk_mul_f32 v[162:163], v[136:137], v[136:137]
	v_pk_mul_f32 v[160:161], v[138:139], v[138:139]
	v_add_f32_e32 v141, v162, v163
	v_add_f32_e32 v141, v160, v141
	v_add_f32_e32 v141, v161, v141
	s_nop 1
	v_readlane_b32 s16, v253, 6
	v_readlane_b32 s17, v253, 7
	s_waitcnt lgkmcnt(0)
	v_add_f32_dpp v141, v141, v141 quad_perm:[1,0,3,2] row_mask:0xf bank_mask:0xf
	s_nop 1
	s_waitcnt lgkmcnt(0)
	v_add_f32_dpp v141, v141, v141 quad_perm:[2,3,0,1] row_mask:0xf bank_mask:0xf
	s_nop 1
	s_waitcnt lgkmcnt(0)
	v_add_f32_dpp v141, v141, v141 row_half_mirror row_mask:0xf bank_mask:0xf
	s_nop 1
	s_waitcnt lgkmcnt(0)
	v_add_f32_dpp v141, v141, v141 row_mirror row_mask:0xf bank_mask:0xf
	v_mov_b32_e32 v159, v141
	s_nop 1
	v_permlane16_swap_b32_e32 v159, v141
	s_waitcnt lgkmcnt(0)
	v_add_f32_e32 v141, v141, v159
	v_fmamk_f32 v141, v141, 0x3c000000, v1
	v_cmp_gt_f32_e32 vcc, s29, v141
	v_mul_f32_e32 v159, 0x4b800000, v141
	s_nop 0
	v_cndmask_b32_e32 v141, v141, v159, vcc
	v_rsq_f32_e32 v141, v141
	s_nop 0
	v_mul_f32_e32 v159, 0x45800000, v141
	v_cndmask_b32_e32 v160, v141, v159, vcc
	v_pk_mul_f32 v[136:137], v[136:137], v[160:161] op_sel_hi:[1,0]
	v_pk_mul_f32 v[138:139], v[138:139], v[160:161] op_sel_hi:[1,0]
	v_pk_mul_f32 v[136:137], v[132:133], v[136:137]
	v_pk_mul_f32 v[138:139], v[134:135], v[138:139]
	s_and_b64 vcc, exec, s[38:39]
	s_cbranch_vccnz .LBB0_331
	v_add_u32_e32 v160, s6, v158
	v_readlane_b32 s0, v251, 28
	v_ashrrev_i32_e32 v161, 31, v160
	s_add_u32 s0, s0, s4
	v_readlane_b32 s1, v251, 29
	s_addc_u32 s1, s1, s5
	v_lshlrev_b64 v[160:161], 9, v[160:161]
	v_lshl_add_u64 v[160:161], s[0:1], 0, v[160:161]
	v_mov_b32_e32 v141, v3
	v_lshl_add_u64 v[160:161], v[160:161], 0, v[140:141]
	global_store_dwordx4 v[160:161], v[136:139], off
.LBB0_331:
	v_add_u32_e32 v158, s83, v158
	v_ashrrev_i32_e32 v159, 31, v158
	v_readlane_b32 s12, v253, 2
	v_lshlrev_b64 v[158:159], 8, v[158:159]
	v_readlane_b32 s18, v253, 8
	v_readlane_b32 s19, v253, 9
	v_cvt_pk_bf16_f32 v136, v136, v137
	v_cvt_pk_bf16_f32 v137, v138, v139
	v_lshl_add_u64 v[158:159], s[18:19], 0, v[158:159]
	v_lshl_add_u64 v[158:159], v[158:159], 0, v[2:3]
	global_store_dwordx2 v[158:159], v[136:137], off sc1
	ds_read_b128 v[136:139], v157 offset:29568
	v_add_u32_e32 v158, 56, v142
	v_readlane_b32 s13, v253, 3
	v_readlane_b32 s14, v253, 4
	v_readlane_b32 s15, v253, 5
	s_waitcnt lgkmcnt(0)
	v_pk_mul_f32 v[162:163], v[136:137], v[136:137]
	v_pk_mul_f32 v[160:161], v[138:139], v[138:139]
	v_add_f32_e32 v141, v162, v163
	v_add_f32_e32 v141, v160, v141
	v_add_f32_e32 v141, v161, v141
	s_nop 1
	v_readlane_b32 s16, v253, 6
	v_readlane_b32 s17, v253, 7
	s_waitcnt lgkmcnt(0)
	v_add_f32_dpp v141, v141, v141 quad_perm:[1,0,3,2] row_mask:0xf bank_mask:0xf
	s_nop 1
	s_waitcnt lgkmcnt(0)
	v_add_f32_dpp v141, v141, v141 quad_perm:[2,3,0,1] row_mask:0xf bank_mask:0xf
	s_nop 1
	s_waitcnt lgkmcnt(0)
	v_add_f32_dpp v141, v141, v141 row_half_mirror row_mask:0xf bank_mask:0xf
	s_nop 1
	s_waitcnt lgkmcnt(0)
	v_add_f32_dpp v141, v141, v141 row_mirror row_mask:0xf bank_mask:0xf
	v_mov_b32_e32 v159, v141
	s_nop 1
	v_permlane16_swap_b32_e32 v159, v141
	s_waitcnt lgkmcnt(0)
	v_add_f32_e32 v141, v141, v159
	v_fmamk_f32 v141, v141, 0x3c000000, v1
	v_cmp_gt_f32_e32 vcc, s29, v141
	v_mul_f32_e32 v159, 0x4b800000, v141
	s_nop 0
	v_cndmask_b32_e32 v141, v141, v159, vcc
	v_rsq_f32_e32 v141, v141
	s_nop 0
	v_mul_f32_e32 v159, 0x45800000, v141
	v_cndmask_b32_e32 v160, v141, v159, vcc
	v_pk_mul_f32 v[136:137], v[136:137], v[160:161] op_sel_hi:[1,0]
	v_pk_mul_f32 v[138:139], v[138:139], v[160:161] op_sel_hi:[1,0]
	v_pk_mul_f32 v[136:137], v[132:133], v[136:137]
	v_pk_mul_f32 v[138:139], v[134:135], v[138:139]
	s_and_b64 vcc, exec, s[38:39]
	s_cbranch_vccnz .LBB0_333
	v_add_u32_e32 v160, s6, v158
	v_readlane_b32 s0, v251, 28
	v_ashrrev_i32_e32 v161, 31, v160
	s_add_u32 s0, s0, s4
	v_readlane_b32 s1, v251, 29
	s_addc_u32 s1, s1, s5
	v_lshlrev_b64 v[160:161], 9, v[160:161]
	v_lshl_add_u64 v[160:161], s[0:1], 0, v[160:161]
	v_mov_b32_e32 v141, v3
	v_lshl_add_u64 v[160:161], v[160:161], 0, v[140:141]
	global_store_dwordx4 v[160:161], v[136:139], off
.LBB0_333:
	v_add_u32_e32 v158, s83, v158
	v_ashrrev_i32_e32 v159, 31, v158
	v_readlane_b32 s12, v253, 2
	v_lshlrev_b64 v[158:159], 8, v[158:159]
	v_readlane_b32 s18, v253, 8
	v_readlane_b32 s19, v253, 9
	v_cvt_pk_bf16_f32 v136, v136, v137
	v_cvt_pk_bf16_f32 v137, v138, v139
	v_lshl_add_u64 v[158:159], s[18:19], 0, v[158:159]
	v_lshl_add_u64 v[158:159], v[158:159], 0, v[2:3]
	global_store_dwordx2 v[158:159], v[136:137], off sc1
	ds_read_b128 v[136:139], v157 offset:33792
	v_add_u32_e32 v158, 64, v142
	v_readlane_b32 s13, v253, 3
	v_readlane_b32 s14, v253, 4
	v_readlane_b32 s15, v253, 5
	s_waitcnt lgkmcnt(0)
	v_pk_mul_f32 v[162:163], v[136:137], v[136:137]
	v_pk_mul_f32 v[160:161], v[138:139], v[138:139]
	v_add_f32_e32 v141, v162, v163
	v_add_f32_e32 v141, v160, v141
	v_add_f32_e32 v141, v161, v141
	s_nop 1
	v_readlane_b32 s16, v253, 6
	v_readlane_b32 s17, v253, 7
	s_waitcnt lgkmcnt(0)
	v_add_f32_dpp v141, v141, v141 quad_perm:[1,0,3,2] row_mask:0xf bank_mask:0xf
	s_nop 1
	s_waitcnt lgkmcnt(0)
	v_add_f32_dpp v141, v141, v141 quad_perm:[2,3,0,1] row_mask:0xf bank_mask:0xf
	s_nop 1
	s_waitcnt lgkmcnt(0)
	v_add_f32_dpp v141, v141, v141 row_half_mirror row_mask:0xf bank_mask:0xf
	s_nop 1
	s_waitcnt lgkmcnt(0)
	v_add_f32_dpp v141, v141, v141 row_mirror row_mask:0xf bank_mask:0xf
	v_mov_b32_e32 v159, v141
	s_nop 1
	v_permlane16_swap_b32_e32 v159, v141
	s_waitcnt lgkmcnt(0)
	v_add_f32_e32 v141, v141, v159
	v_fmamk_f32 v141, v141, 0x3c000000, v1
	v_cmp_gt_f32_e32 vcc, s29, v141
	v_mul_f32_e32 v159, 0x4b800000, v141
	s_nop 0
	v_cndmask_b32_e32 v141, v141, v159, vcc
	v_rsq_f32_e32 v141, v141
	s_nop 0
	v_mul_f32_e32 v159, 0x45800000, v141
	v_cndmask_b32_e32 v160, v141, v159, vcc
	v_pk_mul_f32 v[136:137], v[136:137], v[160:161] op_sel_hi:[1,0]
	v_pk_mul_f32 v[138:139], v[138:139], v[160:161] op_sel_hi:[1,0]
	v_pk_mul_f32 v[136:137], v[132:133], v[136:137]
	v_pk_mul_f32 v[138:139], v[134:135], v[138:139]
	s_and_b64 vcc, exec, s[38:39]
	s_cbranch_vccnz .LBB0_335
	v_add_u32_e32 v160, s6, v158
	v_readlane_b32 s0, v251, 28
	v_ashrrev_i32_e32 v161, 31, v160
	s_add_u32 s0, s0, s4
	v_readlane_b32 s1, v251, 29
	s_addc_u32 s1, s1, s5
	v_lshlrev_b64 v[160:161], 9, v[160:161]
	v_lshl_add_u64 v[160:161], s[0:1], 0, v[160:161]
	v_mov_b32_e32 v141, v3
	v_lshl_add_u64 v[160:161], v[160:161], 0, v[140:141]
	global_store_dwordx4 v[160:161], v[136:139], off
.LBB0_335:
	v_add_u32_e32 v158, s83, v158
	v_ashrrev_i32_e32 v159, 31, v158
	v_readlane_b32 s12, v253, 2
	v_lshlrev_b64 v[158:159], 8, v[158:159]
	v_readlane_b32 s18, v253, 8
	v_readlane_b32 s19, v253, 9
	v_cvt_pk_bf16_f32 v136, v136, v137
	v_cvt_pk_bf16_f32 v137, v138, v139
	v_lshl_add_u64 v[158:159], s[18:19], 0, v[158:159]
	v_lshl_add_u64 v[158:159], v[158:159], 0, v[2:3]
	global_store_dwordx2 v[158:159], v[136:137], off sc1
	ds_read_b128 v[136:139], v157 offset:38016
	v_add_u32_e32 v158, 0x48, v142
	v_readlane_b32 s13, v253, 3
	v_readlane_b32 s14, v253, 4
	v_readlane_b32 s15, v253, 5
	s_waitcnt lgkmcnt(0)
	v_pk_mul_f32 v[162:163], v[136:137], v[136:137]
	v_pk_mul_f32 v[160:161], v[138:139], v[138:139]
	v_add_f32_e32 v141, v162, v163
	v_add_f32_e32 v141, v160, v141
	v_add_f32_e32 v141, v161, v141
	s_nop 1
	v_readlane_b32 s16, v253, 6
	v_readlane_b32 s17, v253, 7
	s_waitcnt lgkmcnt(0)
	v_add_f32_dpp v141, v141, v141 quad_perm:[1,0,3,2] row_mask:0xf bank_mask:0xf
	s_nop 1
	s_waitcnt lgkmcnt(0)
	v_add_f32_dpp v141, v141, v141 quad_perm:[2,3,0,1] row_mask:0xf bank_mask:0xf
	s_nop 1
	s_waitcnt lgkmcnt(0)
	v_add_f32_dpp v141, v141, v141 row_half_mirror row_mask:0xf bank_mask:0xf
	s_nop 1
	s_waitcnt lgkmcnt(0)
	v_add_f32_dpp v141, v141, v141 row_mirror row_mask:0xf bank_mask:0xf
	v_mov_b32_e32 v159, v141
	s_nop 1
	v_permlane16_swap_b32_e32 v159, v141
	s_waitcnt lgkmcnt(0)
	v_add_f32_e32 v141, v141, v159
	v_fmamk_f32 v141, v141, 0x3c000000, v1
	v_cmp_gt_f32_e32 vcc, s29, v141
	v_mul_f32_e32 v159, 0x4b800000, v141
	s_nop 0
	v_cndmask_b32_e32 v141, v141, v159, vcc
	v_rsq_f32_e32 v141, v141
	s_nop 0
	v_mul_f32_e32 v159, 0x45800000, v141
	v_cndmask_b32_e32 v160, v141, v159, vcc
	v_pk_mul_f32 v[136:137], v[136:137], v[160:161] op_sel_hi:[1,0]
	v_pk_mul_f32 v[138:139], v[138:139], v[160:161] op_sel_hi:[1,0]
	v_pk_mul_f32 v[136:137], v[132:133], v[136:137]
	v_pk_mul_f32 v[138:139], v[134:135], v[138:139]
	s_and_b64 vcc, exec, s[38:39]
	s_cbranch_vccnz .LBB0_337
	v_add_u32_e32 v160, s6, v158
	v_readlane_b32 s0, v251, 28
	v_ashrrev_i32_e32 v161, 31, v160
	s_add_u32 s0, s0, s4
	v_readlane_b32 s1, v251, 29
	s_addc_u32 s1, s1, s5
	v_lshlrev_b64 v[160:161], 9, v[160:161]
	v_lshl_add_u64 v[160:161], s[0:1], 0, v[160:161]
	v_mov_b32_e32 v141, v3
	v_lshl_add_u64 v[160:161], v[160:161], 0, v[140:141]
	global_store_dwordx4 v[160:161], v[136:139], off
.LBB0_337:
	v_add_u32_e32 v158, s83, v158
	v_ashrrev_i32_e32 v159, 31, v158
	v_readlane_b32 s12, v253, 2
	v_lshlrev_b64 v[158:159], 8, v[158:159]
	v_readlane_b32 s18, v253, 8
	v_readlane_b32 s19, v253, 9
	v_cvt_pk_bf16_f32 v136, v136, v137
	v_cvt_pk_bf16_f32 v137, v138, v139
	v_lshl_add_u64 v[158:159], s[18:19], 0, v[158:159]
	v_lshl_add_u64 v[158:159], v[158:159], 0, v[2:3]
	global_store_dwordx2 v[158:159], v[136:137], off sc1
	ds_read_b128 v[136:139], v157 offset:42240
	v_add_u32_e32 v158, 0x50, v142
	v_readlane_b32 s13, v253, 3
	v_readlane_b32 s14, v253, 4
	v_readlane_b32 s15, v253, 5
	s_waitcnt lgkmcnt(0)
	v_pk_mul_f32 v[162:163], v[136:137], v[136:137]
	v_pk_mul_f32 v[160:161], v[138:139], v[138:139]
	v_add_f32_e32 v141, v162, v163
	v_add_f32_e32 v141, v160, v141
	v_add_f32_e32 v141, v161, v141
	s_nop 1
	v_readlane_b32 s16, v253, 6
	v_readlane_b32 s17, v253, 7
	s_waitcnt lgkmcnt(0)
	v_add_f32_dpp v141, v141, v141 quad_perm:[1,0,3,2] row_mask:0xf bank_mask:0xf
	s_nop 1
	s_waitcnt lgkmcnt(0)
	v_add_f32_dpp v141, v141, v141 quad_perm:[2,3,0,1] row_mask:0xf bank_mask:0xf
	s_nop 1
	s_waitcnt lgkmcnt(0)
	v_add_f32_dpp v141, v141, v141 row_half_mirror row_mask:0xf bank_mask:0xf
	s_nop 1
	s_waitcnt lgkmcnt(0)
	v_add_f32_dpp v141, v141, v141 row_mirror row_mask:0xf bank_mask:0xf
	v_mov_b32_e32 v159, v141
	s_nop 1
	v_permlane16_swap_b32_e32 v159, v141
	s_waitcnt lgkmcnt(0)
	v_add_f32_e32 v141, v141, v159
	v_fmamk_f32 v141, v141, 0x3c000000, v1
	v_cmp_gt_f32_e32 vcc, s29, v141
	v_mul_f32_e32 v159, 0x4b800000, v141
	s_nop 0
	v_cndmask_b32_e32 v141, v141, v159, vcc
	v_rsq_f32_e32 v141, v141
	s_nop 0
	v_mul_f32_e32 v159, 0x45800000, v141
	v_cndmask_b32_e32 v160, v141, v159, vcc
	v_pk_mul_f32 v[136:137], v[136:137], v[160:161] op_sel_hi:[1,0]
	v_pk_mul_f32 v[138:139], v[138:139], v[160:161] op_sel_hi:[1,0]
	v_pk_mul_f32 v[136:137], v[132:133], v[136:137]
	v_pk_mul_f32 v[138:139], v[134:135], v[138:139]
	s_and_b64 vcc, exec, s[38:39]
	s_cbranch_vccnz .LBB0_339
	v_add_u32_e32 v160, s6, v158
	v_readlane_b32 s0, v251, 28
	v_ashrrev_i32_e32 v161, 31, v160
	s_add_u32 s0, s0, s4
	v_readlane_b32 s1, v251, 29
	s_addc_u32 s1, s1, s5
	v_lshlrev_b64 v[160:161], 9, v[160:161]
	v_lshl_add_u64 v[160:161], s[0:1], 0, v[160:161]
	v_mov_b32_e32 v141, v3
	v_lshl_add_u64 v[160:161], v[160:161], 0, v[140:141]
	global_store_dwordx4 v[160:161], v[136:139], off
.LBB0_339:
	v_add_u32_e32 v158, s83, v158
	v_ashrrev_i32_e32 v159, 31, v158
	v_readlane_b32 s12, v253, 2
	v_lshlrev_b64 v[158:159], 8, v[158:159]
	v_readlane_b32 s18, v253, 8
	v_readlane_b32 s19, v253, 9
	v_cvt_pk_bf16_f32 v136, v136, v137
	v_cvt_pk_bf16_f32 v137, v138, v139
	v_lshl_add_u64 v[158:159], s[18:19], 0, v[158:159]
	v_lshl_add_u64 v[158:159], v[158:159], 0, v[2:3]
	global_store_dwordx2 v[158:159], v[136:137], off sc1
	ds_read_b128 v[136:139], v157 offset:46464
	v_add_u32_e32 v158, 0x58, v142
	v_readlane_b32 s13, v253, 3
	v_readlane_b32 s14, v253, 4
	v_readlane_b32 s15, v253, 5
	s_waitcnt lgkmcnt(0)
	v_pk_mul_f32 v[162:163], v[136:137], v[136:137]
	v_pk_mul_f32 v[160:161], v[138:139], v[138:139]
	v_add_f32_e32 v141, v162, v163
	v_add_f32_e32 v141, v160, v141
	v_add_f32_e32 v141, v161, v141
	s_nop 1
	v_readlane_b32 s16, v253, 6
	v_readlane_b32 s17, v253, 7
	s_waitcnt lgkmcnt(0)
	v_add_f32_dpp v141, v141, v141 quad_perm:[1,0,3,2] row_mask:0xf bank_mask:0xf
	s_nop 1
	s_waitcnt lgkmcnt(0)
	v_add_f32_dpp v141, v141, v141 quad_perm:[2,3,0,1] row_mask:0xf bank_mask:0xf
	s_nop 1
	s_waitcnt lgkmcnt(0)
	v_add_f32_dpp v141, v141, v141 row_half_mirror row_mask:0xf bank_mask:0xf
	s_nop 1
	s_waitcnt lgkmcnt(0)
	v_add_f32_dpp v141, v141, v141 row_mirror row_mask:0xf bank_mask:0xf
	v_mov_b32_e32 v159, v141
	s_nop 1
	v_permlane16_swap_b32_e32 v159, v141
	s_waitcnt lgkmcnt(0)
	v_add_f32_e32 v141, v141, v159
	v_fmamk_f32 v141, v141, 0x3c000000, v1
	v_cmp_gt_f32_e32 vcc, s29, v141
	v_mul_f32_e32 v159, 0x4b800000, v141
	s_nop 0
	v_cndmask_b32_e32 v141, v141, v159, vcc
	v_rsq_f32_e32 v141, v141
	s_nop 0
	v_mul_f32_e32 v159, 0x45800000, v141
	v_cndmask_b32_e32 v160, v141, v159, vcc
	v_pk_mul_f32 v[136:137], v[136:137], v[160:161] op_sel_hi:[1,0]
	v_pk_mul_f32 v[138:139], v[138:139], v[160:161] op_sel_hi:[1,0]
	v_pk_mul_f32 v[136:137], v[132:133], v[136:137]
	v_pk_mul_f32 v[138:139], v[134:135], v[138:139]
	s_and_b64 vcc, exec, s[38:39]
	s_cbranch_vccnz .LBB0_341
	v_add_u32_e32 v160, s6, v158
	v_readlane_b32 s0, v251, 28
	v_ashrrev_i32_e32 v161, 31, v160
	s_add_u32 s0, s0, s4
	v_readlane_b32 s1, v251, 29
	s_addc_u32 s1, s1, s5
	v_lshlrev_b64 v[160:161], 9, v[160:161]
	v_lshl_add_u64 v[160:161], s[0:1], 0, v[160:161]
	v_mov_b32_e32 v141, v3
	v_lshl_add_u64 v[160:161], v[160:161], 0, v[140:141]
	global_store_dwordx4 v[160:161], v[136:139], off
.LBB0_341:
	v_add_u32_e32 v158, s83, v158
	v_ashrrev_i32_e32 v159, 31, v158
	v_readlane_b32 s12, v253, 2
	v_lshlrev_b64 v[158:159], 8, v[158:159]
	v_readlane_b32 s18, v253, 8
	v_readlane_b32 s19, v253, 9
	v_cvt_pk_bf16_f32 v136, v136, v137
	v_cvt_pk_bf16_f32 v137, v138, v139
	v_lshl_add_u64 v[158:159], s[18:19], 0, v[158:159]
	v_lshl_add_u64 v[158:159], v[158:159], 0, v[2:3]
	global_store_dwordx2 v[158:159], v[136:137], off sc1
	ds_read_b128 v[136:139], v157 offset:50688
	v_add_u32_e32 v158, 0x60, v142
	v_readlane_b32 s13, v253, 3
	v_readlane_b32 s14, v253, 4
	v_readlane_b32 s15, v253, 5
	s_waitcnt lgkmcnt(0)
	v_pk_mul_f32 v[162:163], v[136:137], v[136:137]
	v_pk_mul_f32 v[160:161], v[138:139], v[138:139]
	v_add_f32_e32 v141, v162, v163
	v_add_f32_e32 v141, v160, v141
	v_add_f32_e32 v141, v161, v141
	s_nop 1
	v_readlane_b32 s16, v253, 6
	v_readlane_b32 s17, v253, 7
	s_waitcnt lgkmcnt(0)
	v_add_f32_dpp v141, v141, v141 quad_perm:[1,0,3,2] row_mask:0xf bank_mask:0xf
	s_nop 1
	s_waitcnt lgkmcnt(0)
	v_add_f32_dpp v141, v141, v141 quad_perm:[2,3,0,1] row_mask:0xf bank_mask:0xf
	s_nop 1
	s_waitcnt lgkmcnt(0)
	v_add_f32_dpp v141, v141, v141 row_half_mirror row_mask:0xf bank_mask:0xf
	s_nop 1
	s_waitcnt lgkmcnt(0)
	v_add_f32_dpp v141, v141, v141 row_mirror row_mask:0xf bank_mask:0xf
	v_mov_b32_e32 v159, v141
	s_nop 1
	v_permlane16_swap_b32_e32 v159, v141
	s_waitcnt lgkmcnt(0)
	v_add_f32_e32 v141, v141, v159
	v_fmamk_f32 v141, v141, 0x3c000000, v1
	v_cmp_gt_f32_e32 vcc, s29, v141
	v_mul_f32_e32 v159, 0x4b800000, v141
	s_nop 0
	v_cndmask_b32_e32 v141, v141, v159, vcc
	v_rsq_f32_e32 v141, v141
	s_nop 0
	v_mul_f32_e32 v159, 0x45800000, v141
	v_cndmask_b32_e32 v160, v141, v159, vcc
	v_pk_mul_f32 v[136:137], v[136:137], v[160:161] op_sel_hi:[1,0]
	v_pk_mul_f32 v[138:139], v[138:139], v[160:161] op_sel_hi:[1,0]
	v_pk_mul_f32 v[136:137], v[132:133], v[136:137]
	v_pk_mul_f32 v[138:139], v[134:135], v[138:139]
	s_and_b64 vcc, exec, s[38:39]
	s_cbranch_vccnz .LBB0_343
	v_add_u32_e32 v160, s6, v158
	v_readlane_b32 s0, v251, 28
	v_ashrrev_i32_e32 v161, 31, v160
	s_add_u32 s0, s0, s4
	v_readlane_b32 s1, v251, 29
	s_addc_u32 s1, s1, s5
	v_lshlrev_b64 v[160:161], 9, v[160:161]
	v_lshl_add_u64 v[160:161], s[0:1], 0, v[160:161]
	v_mov_b32_e32 v141, v3
	v_lshl_add_u64 v[160:161], v[160:161], 0, v[140:141]
	global_store_dwordx4 v[160:161], v[136:139], off
.LBB0_343:
	v_add_u32_e32 v158, s83, v158
	v_ashrrev_i32_e32 v159, 31, v158
	v_readlane_b32 s12, v253, 2
	v_lshlrev_b64 v[158:159], 8, v[158:159]
	v_readlane_b32 s18, v253, 8
	v_readlane_b32 s19, v253, 9
	v_cvt_pk_bf16_f32 v136, v136, v137
	v_cvt_pk_bf16_f32 v137, v138, v139
	v_lshl_add_u64 v[158:159], s[18:19], 0, v[158:159]
	v_lshl_add_u64 v[158:159], v[158:159], 0, v[2:3]
	global_store_dwordx2 v[158:159], v[136:137], off sc1
	ds_read_b128 v[136:139], v157 offset:54912
	v_add_u32_e32 v158, 0x68, v142
	v_readlane_b32 s13, v253, 3
	v_readlane_b32 s14, v253, 4
	v_readlane_b32 s15, v253, 5
	s_waitcnt lgkmcnt(0)
	v_pk_mul_f32 v[162:163], v[136:137], v[136:137]
	v_pk_mul_f32 v[160:161], v[138:139], v[138:139]
	v_add_f32_e32 v141, v162, v163
	v_add_f32_e32 v141, v160, v141
	v_add_f32_e32 v141, v161, v141
	s_nop 1
	v_readlane_b32 s16, v253, 6
	v_readlane_b32 s17, v253, 7
	s_waitcnt lgkmcnt(0)
	v_add_f32_dpp v141, v141, v141 quad_perm:[1,0,3,2] row_mask:0xf bank_mask:0xf
	s_nop 1
	s_waitcnt lgkmcnt(0)
	v_add_f32_dpp v141, v141, v141 quad_perm:[2,3,0,1] row_mask:0xf bank_mask:0xf
	s_nop 1
	s_waitcnt lgkmcnt(0)
	v_add_f32_dpp v141, v141, v141 row_half_mirror row_mask:0xf bank_mask:0xf
	s_nop 1
	s_waitcnt lgkmcnt(0)
	v_add_f32_dpp v141, v141, v141 row_mirror row_mask:0xf bank_mask:0xf
	v_mov_b32_e32 v159, v141
	s_nop 1
	v_permlane16_swap_b32_e32 v159, v141
	s_waitcnt lgkmcnt(0)
	v_add_f32_e32 v141, v141, v159
	v_fmamk_f32 v141, v141, 0x3c000000, v1
	v_cmp_gt_f32_e32 vcc, s29, v141
	v_mul_f32_e32 v159, 0x4b800000, v141
	s_nop 0
	v_cndmask_b32_e32 v141, v141, v159, vcc
	v_rsq_f32_e32 v141, v141
	s_nop 0
	v_mul_f32_e32 v159, 0x45800000, v141
	v_cndmask_b32_e32 v160, v141, v159, vcc
	v_pk_mul_f32 v[136:137], v[136:137], v[160:161] op_sel_hi:[1,0]
	v_pk_mul_f32 v[138:139], v[138:139], v[160:161] op_sel_hi:[1,0]
	v_pk_mul_f32 v[136:137], v[132:133], v[136:137]
	v_pk_mul_f32 v[138:139], v[134:135], v[138:139]
	s_and_b64 vcc, exec, s[38:39]
	s_cbranch_vccnz .LBB0_345
	v_add_u32_e32 v160, s6, v158
	v_readlane_b32 s0, v251, 28
	v_ashrrev_i32_e32 v161, 31, v160
	s_add_u32 s0, s0, s4
	v_readlane_b32 s1, v251, 29
	s_addc_u32 s1, s1, s5
	v_lshlrev_b64 v[160:161], 9, v[160:161]
	v_lshl_add_u64 v[160:161], s[0:1], 0, v[160:161]
	v_mov_b32_e32 v141, v3
	v_lshl_add_u64 v[160:161], v[160:161], 0, v[140:141]
	global_store_dwordx4 v[160:161], v[136:139], off
.LBB0_345:
	v_add_u32_e32 v158, s83, v158
	v_ashrrev_i32_e32 v159, 31, v158
	v_readlane_b32 s12, v253, 2
	v_lshlrev_b64 v[158:159], 8, v[158:159]
	v_readlane_b32 s18, v253, 8
	v_readlane_b32 s19, v253, 9
	v_cvt_pk_bf16_f32 v136, v136, v137
	v_cvt_pk_bf16_f32 v137, v138, v139
	v_lshl_add_u64 v[158:159], s[18:19], 0, v[158:159]
	v_lshl_add_u64 v[158:159], v[158:159], 0, v[2:3]
	global_store_dwordx2 v[158:159], v[136:137], off sc1
	ds_read_b128 v[136:139], v157 offset:59136
	v_add_u32_e32 v158, 0x70, v142
	v_readlane_b32 s13, v253, 3
	v_readlane_b32 s14, v253, 4
	v_readlane_b32 s15, v253, 5
	s_waitcnt lgkmcnt(0)
	v_pk_mul_f32 v[162:163], v[136:137], v[136:137]
	v_pk_mul_f32 v[160:161], v[138:139], v[138:139]
	v_add_f32_e32 v141, v162, v163
	v_add_f32_e32 v141, v160, v141
	v_add_f32_e32 v141, v161, v141
	s_nop 1
	v_readlane_b32 s16, v253, 6
	v_readlane_b32 s17, v253, 7
	s_waitcnt lgkmcnt(0)
	v_add_f32_dpp v141, v141, v141 quad_perm:[1,0,3,2] row_mask:0xf bank_mask:0xf
	s_nop 1
	s_waitcnt lgkmcnt(0)
	v_add_f32_dpp v141, v141, v141 quad_perm:[2,3,0,1] row_mask:0xf bank_mask:0xf
	s_nop 1
	s_waitcnt lgkmcnt(0)
	v_add_f32_dpp v141, v141, v141 row_half_mirror row_mask:0xf bank_mask:0xf
	s_nop 1
	s_waitcnt lgkmcnt(0)
	v_add_f32_dpp v141, v141, v141 row_mirror row_mask:0xf bank_mask:0xf
	v_mov_b32_e32 v159, v141
	s_nop 1
	v_permlane16_swap_b32_e32 v159, v141
	s_waitcnt lgkmcnt(0)
	v_add_f32_e32 v141, v141, v159
	v_fmamk_f32 v141, v141, 0x3c000000, v1
	v_cmp_gt_f32_e32 vcc, s29, v141
	v_mul_f32_e32 v159, 0x4b800000, v141
	s_nop 0
	v_cndmask_b32_e32 v141, v141, v159, vcc
	v_rsq_f32_e32 v141, v141
	s_nop 0
	v_mul_f32_e32 v159, 0x45800000, v141
	v_cndmask_b32_e32 v160, v141, v159, vcc
	v_pk_mul_f32 v[136:137], v[136:137], v[160:161] op_sel_hi:[1,0]
	v_pk_mul_f32 v[138:139], v[138:139], v[160:161] op_sel_hi:[1,0]
	v_pk_mul_f32 v[136:137], v[132:133], v[136:137]
	v_pk_mul_f32 v[138:139], v[134:135], v[138:139]
	s_and_b64 vcc, exec, s[38:39]
	s_cbranch_vccnz .LBB0_347
	v_add_u32_e32 v160, s6, v158
	v_readlane_b32 s0, v251, 28
	v_ashrrev_i32_e32 v161, 31, v160
	s_add_u32 s0, s0, s4
	v_readlane_b32 s1, v251, 29
	s_addc_u32 s1, s1, s5
	v_lshlrev_b64 v[160:161], 9, v[160:161]
	v_lshl_add_u64 v[160:161], s[0:1], 0, v[160:161]
	v_mov_b32_e32 v141, v3
	v_lshl_add_u64 v[160:161], v[160:161], 0, v[140:141]
	global_store_dwordx4 v[160:161], v[136:139], off
.LBB0_347:
	ds_read_b128 v[160:163], v157 offset:63360
	v_readlane_b32 s12, v253, 2
	v_cvt_pk_bf16_f32 v159, v138, v139
	v_readlane_b32 s18, v253, 8
	v_readlane_b32 s19, v253, 9
	s_waitcnt lgkmcnt(0)
	v_pk_mul_f32 v[166:167], v[160:161], v[160:161]
	v_pk_mul_f32 v[164:165], v[162:163], v[162:163]
	v_add_f32_e32 v141, v166, v167
	v_add_f32_e32 v141, v164, v141
	v_add_f32_e32 v141, v165, v141
	s_nop 1
	s_and_b64 vcc, exec, s[38:39]
	v_readlane_b32 s13, v253, 3
	v_readlane_b32 s14, v253, 4
	v_readlane_b32 s15, v253, 5
	s_waitcnt lgkmcnt(0)
	v_add_f32_dpp v141, v141, v141 quad_perm:[1,0,3,2] row_mask:0xf bank_mask:0xf
	s_nop 1
	v_add_u32_e32 v152, s83, v158
	v_cvt_pk_bf16_f32 v158, v136, v137
	v_add_u32_e32 v136, 0x78, v142
	v_readlane_b32 s16, v253, 6
	s_waitcnt lgkmcnt(0)
	v_add_f32_dpp v141, v141, v141 quad_perm:[2,3,0,1] row_mask:0xf bank_mask:0xf
	s_nop 1
	v_ashrrev_i32_e32 v153, 31, v152
	v_lshlrev_b64 v[138:139], 8, v[152:153]
	v_lshl_add_u64 v[138:139], s[18:19], 0, v[138:139]
	v_lshl_add_u64 v[138:139], v[138:139], 0, v[2:3]
	s_waitcnt lgkmcnt(0)
	v_add_f32_dpp v141, v141, v141 row_half_mirror row_mask:0xf bank_mask:0xf
	s_nop 1
	global_store_dwordx2 v[138:139], v[158:159], off sc1
	v_readlane_b32 s17, v253, 7
	s_waitcnt lgkmcnt(0)
	v_add_f32_dpp v137, v141, v141 row_mirror row_mask:0xf bank_mask:0xf
	v_mov_b32_e32 v141, v137
	s_nop 1
	v_permlane16_swap_b32_e32 v141, v137
	s_waitcnt lgkmcnt(0)
	v_add_f32_e32 v137, v137, v141
	v_fmamk_f32 v137, v137, 0x3c000000, v1
	v_mul_f32_e32 v141, 0x4b800000, v137
	v_cmp_gt_f32_e64 s[0:1], s29, v137
	s_nop 1
	v_cndmask_b32_e64 v137, v137, v141, s[0:1]
	v_rsq_f32_e32 v137, v137
	s_nop 0
	v_mul_f32_e32 v138, 0x45800000, v137
	v_cndmask_b32_e64 v138, v137, v138, s[0:1]
	v_pk_mul_f32 v[142:143], v[160:161], v[138:139] op_sel_hi:[1,0]
	v_pk_mul_f32 v[138:139], v[162:163], v[138:139] op_sel_hi:[1,0]
	v_pk_mul_f32 v[132:133], v[132:133], v[142:143]
	v_pk_mul_f32 v[134:135], v[134:135], v[138:139]
	s_cbranch_vccnz .LBB0_349
	v_add_u32_e32 v138, s6, v136
	v_readlane_b32 s0, v251, 28
	v_ashrrev_i32_e32 v139, 31, v138
	s_add_u32 s0, s0, s4
	v_readlane_b32 s1, v251, 29
	s_addc_u32 s1, s1, s5
	v_lshlrev_b64 v[138:139], 9, v[138:139]
	v_lshl_add_u64 v[138:139], s[0:1], 0, v[138:139]
	v_mov_b32_e32 v141, v3
	v_lshl_add_u64 v[138:139], v[138:139], 0, v[140:141]
	global_store_dwordx4 v[138:139], v[132:135], off
.LBB0_349:
	v_add_u32_e32 v136, s83, v136
	v_ashrrev_i32_e32 v137, 31, v136
	v_readlane_b32 s12, v253, 2
	v_lshlrev_b64 v[136:137], 8, v[136:137]
	v_readlane_b32 s18, v253, 8
	v_readlane_b32 s19, v253, 9
	v_cvt_pk_bf16_f32 v132, v132, v133
	v_cvt_pk_bf16_f32 v133, v134, v135
	v_lshl_add_u64 v[136:137], s[18:19], 0, v[136:137]
	v_lshl_add_u64 v[136:137], v[136:137], 0, v[2:3]
	v_readlane_b32 s13, v253, 3
	v_readlane_b32 s14, v253, 4
	v_readlane_b32 s15, v253, 5
	v_readlane_b32 s16, v253, 6
	v_readlane_b32 s17, v253, 7
	global_store_dwordx2 v[136:137], v[132:133], off sc1

.LBB0_414:
	s_and_b32 s0, s77, 0xffffff80
	s_cmpk_lg_i32 s0, 0x480
	s_movk_i32 s36, 0x1fff
	s_cbranch_scc1 .LBB0_419
	s_waitcnt vmcnt(0)
	s_barrier
	s_mov_b64 s[0:1], exec
	v_readlane_b32 s2, v252, 58
	v_readlane_b32 s3, v252, 59
	s_and_b64 s[2:3], s[0:1], s[2:3]
	s_mov_b64 exec, s[2:3]
	s_cbranch_execz .LBB0_418
	s_mov_b64 s[2:3], exec
	v_mbcnt_lo_u32_b32 v2, s2, 0
	s_waitcnt vmcnt(0)
	s_waitcnt vmcnt(0)
	v_mbcnt_hi_u32_b32 v2, s3, v2
	v_cmp_eq_u32_e32 vcc, 0, v2
	s_and_b64 s[4:5], exec, vcc
	s_mov_b64 exec, s[4:5]
	s_cbranch_execz .LBB0_418
	s_or_b32 s4, s85, s87
	s_ashr_i32 s5, s4, 31
	s_lshl_b64 s[4:5], s[4:5], 2
	s_add_u32 s4, s64, s4
	s_addc_u32 s5, s65, s5
	s_bcnt1_i32_b64 s2, s[2:3]
	v_mov_b32_e32 v2, s2
	global_atomic_add v3, v2, s[4:5]
